# DSA tile loop: 4-slot K/V ring and wave stagger (waves 4-7 take the per-tile barrier after the S MFMAs, waves 0-3 inside PV), item-end barrier
# baseline (speedup 1.0000x reference)
; template <int DQK, int W1, int DV, int VW, int MODE> ...
;     ...
;   bf16x8 qf[ND];
; #pragma unroll
;   for (int d0 = 0; d0 < ND; ++d0) qf[d0] = *(const bf16x8*)(qrow + d0 * 16 + hi * 8);
;   f32x16 o[NCB];
; #pragma unroll
;   for (int cb = 0; cb < NCB; ++cb)
; #pragma unroll
;     for (int r = 0; r < 16; ++r) o[cb][r] = 0.f;
;   f32x16 negm = {0.f, 0.f, 0.f, 0.f, 0.f, 0.f, 0.f, 0.f, 0.f, 0.f, 0.f, 0.f, 0.f, 0.f, 0.f, 0.f};
;   float m = m_init, l = (hi == 0) ? l_init : 0.f;
;   const unsigned klane = (unsigned)(r32 * KSTR + hi * 16);
;   const unsigned vlane = (unsigned)(64 * KSTR + vcb0 * 4096 + ((lane >> 4) & 1) * 32 + (lane & 3) * 8 + (4 * hi + ((lane & 15) >> 2)) * 64);
;   unsigned mwn[2] = {0u, 0u};
;     ...
;   stage_tile(kbase0, 0);
;   asm volatile("s_waitcnt vmcnt(0)" ::: "memory");
;   __syncthreads();
.Ldsa_p1_done:
	v_lshlrev_b32_e32 v210, 2, v82
	s_lshl_b32 s100, s29, 5
	v_add_u32_e32 v210, s100, v210
	v_mov_b32_e32 v211, v1
	v_lshl_add_u64 v[210:211], v[96:97], 0, v[210:211]
	s_add_i32 m0, s18, 0x11000
	v_and_b32_e32 v208, 31, v179
	global_load_lds_dwordx4 v[210:211], off
	v_lshlrev_b32_e32 v208, 4, v208
	v_add_u32_e32 v208, 0x11000, v208
	s_waitcnt vmcnt(0)
	v_or3_b32 v99, v0, v2, s0
	v_mov_b32_e32 v0, v1
	v_mov_b32_e32 v2, v1
	v_mov_b32_e32 v3, v1
	v_mov_b32_e32 v4, v1
	v_mov_b32_e32 v5, v1
	v_mov_b32_e32 v6, v1
	v_mov_b32_e32 v7, v1
	v_mov_b32_e32 v8, v1
	v_mov_b32_e32 v9, v1
	v_mov_b32_e32 v10, v1
	v_mov_b32_e32 v11, v1
	v_mov_b32_e32 v12, v1
	v_mov_b32_e32 v13, v1
	v_mov_b64_e32 v[32:33], v[14:15]
	v_mov_b64_e32 v[30:31], v[12:13]
	v_mov_b64_e32 v[28:29], v[10:11]
	v_mov_b64_e32 v[26:27], v[8:9]
	v_mov_b64_e32 v[24:25], v[6:7]
	v_mov_b64_e32 v[22:23], v[4:5]
	v_mov_b64_e32 v[20:21], v[2:3]
	v_mov_b64_e32 v[18:19], v[0:1]
	v_mov_b64_e32 v[16:17], v[14:15]
	s_add_i32 s73, s18, 0
	s_add_i32 s86, s28, 0x7a1
	s_waitcnt lgkmcnt(0)
	v_mov_b32_e32 v89, v88
	s_add_i32 s87, s69, 1
	v_sub_u32_e32 v118, v247, v82
	s_mov_b32 s0, 0
	v_mov_b32_e32 v119, 0
	v_mov_b32_e32 v98, 0xefa18f08
	s_mov_b32 s94, 64
	v_mov_b64_e32 v[14:15], v[12:13]
	v_mov_b64_e32 v[12:13], v[10:11]
	v_mov_b64_e32 v[10:11], v[8:9]
	v_mov_b64_e32 v[8:9], v[6:7]
	v_mov_b64_e32 v[6:7], v[4:5]
	v_mov_b64_e32 v[4:5], v[2:3]
	v_mov_b64_e32 v[2:3], v[0:1]
	s_mov_b64 s[28:29], 0xf4000
	s_mov_b32 s100, 0
	s_mov_b32 s101, 0x8800
	s_waitcnt vmcnt(0)
	s_barrier
	s_add_i32 s95, s0, 1
	s_cmp_ge_u32 s0, s69
	s_cbranch_scc1 .LBB0_1333

; DI int crow(int reg, int hi) { return (reg & 3) + 8 * (reg >> 2) + 4 * hi; }
; template <int DQK, int W1, int DV, int VW, int MODE> ...
;     ...
;   for (int t = 0; t < ntiles; ++t) {
;     const int kb = kbase0 + t * 64;
;     const unsigned bufa = lds0 + (unsigned)((t & 1) * BUF);
;     const unsigned mw0 = mwn[0], mw1 = mwn[1];
;     if (t + 1 < ntiles) stage_tile(kb + 64, (t + 1) & 1);
;     if (!(MODE == 0 && kb > tq0 + 31)) {
;       f32x16 s[2];
;       s[0] = s_block<KSTR, ND, 0>(bufa + klane, qf, negm);
;       s[1] = s_block<KSTR, ND, 1>(bufa + klane, qf, negm);
;       if (MODE == 0) {
;         if (__builtin_amdgcn_readfirstlane((int)(kb + 63 > tq0))) {
; #pragma unroll
;           for (int n = 0; n < 2; ++n)
; #pragma unroll
;             for (int i = 0; i < 16; ++i) { const int key = kb + 32 * n + crow(i, hi); if (key > tq) s[n][i] = NEGV; }
;         }
;       } else if (MODE == 1) {
;         const bool far = (tq0 - (kb + 63)) >= 128;
; #pragma unroll
;         for (int n = 0; n < 2; ++n) {
;           const unsigned wb = (n ? mw1 : mw0) >> (4 * hi);
;           if (far) {
; #pragma unroll
;             for (int i = 0; i < 16; ++i) {
;               const float v = fmaf(s[n][i], c2, bias_far);
;               s[n][i] = ((wb >> ((i & 3) + 8 * (i >> 2))) & 1u) ? v : NEGV;
;             }
;           } else {
; #pragma unroll
;             for (int i = 0; i < 16; ++i) {
;               const int key = kb + 32 * n + crow(i, hi);
;               int rel = tq - key; rel = rel < 0 ? 0 : (rel > 128 ? 128 : rel);
;               const float v = fmaf(s[n][i], c2, lutw[rel]);
;               s[n][i] = ((wb >> ((i & 3) + 8 * (i >> 2))) & 1u) ? v : NEGV;
;             }
;           }
.LBB0_1334:
	s_mov_b32 s54, s100
	v_add_u32_e32 v0, s54, v83
	ds_read_b128 v[34:37], v0
	ds_read_b128 v[38:41], v0 offset:32
	ds_read_b128 v[42:45], v0 offset:64
	ds_read_b128 v[46:49], v0 offset:96
	ds_read_b128 v[212:215], v0 offset:4608
	ds_read_b128 v[102:105], v0 offset:4640
	ds_read_b128 v[106:109], v0 offset:4672
	ds_read_b128 v[110:113], v0 offset:4704
	v_lshrrev_b32_e32 v121, v82, v116
	s_cmpk_lt_i32 s86, 0x80
	s_cselect_b64 s[18:19], -1, 0
	s_cmpk_gt_i32 s86, 0x7f
	s_mov_b64 s[0:1], -1
	s_waitcnt lgkmcnt(7)
	v_mfma_f32_32x32x16_bf16 v[50:65], v[34:37], v[66:69], 0
	v_add_u32_e32 v0, s86, v118
	s_waitcnt lgkmcnt(6)
	v_mfma_f32_32x32x16_bf16 v[50:65], v[38:41], v[70:73], v[50:65]
	s_waitcnt lgkmcnt(5)
	v_mfma_f32_32x32x16_bf16 v[50:65], v[42:45], v[74:77], v[50:65]
	s_waitcnt lgkmcnt(4)
	v_mfma_f32_32x32x16_bf16 v[50:65], v[46:49], v[78:81], v[50:65]
	s_waitcnt lgkmcnt(3)
	v_mfma_f32_32x32x16_bf16 v[34:49], v[212:215], v[66:69], 0
	s_waitcnt lgkmcnt(2)
	v_mfma_f32_32x32x16_bf16 v[34:49], v[102:105], v[70:73], v[34:49]
	s_waitcnt lgkmcnt(1)
	v_mfma_f32_32x32x16_bf16 v[34:49], v[106:109], v[74:77], v[34:49]
	s_waitcnt lgkmcnt(0)
	v_mfma_f32_32x32x16_bf16 v[34:49], v[110:113], v[78:81], v[34:49]
	s_cmp_lt_u32 s73, 0x1000
	s_cbranch_scc1 .Ldsa_sa
	s_cmp_ge_u32 s95, s69
	s_cbranch_scc1 .Ldsa_sb0
	s_waitcnt vmcnt(2)
	s_branch .Ldsa_sb
.Ldsa_sb0:
	s_waitcnt vmcnt(0)
.Ldsa_sb:
	s_barrier
.Ldsa_sa:
	s_cmpk_gt_i32 s86, 0x7f
	s_cbranch_scc1 .LBB0_1336
	v_and_b32_e32 v122, 0x4000000, v121
	v_and_b32_e32 v135, 2, v121
	v_and_b32_e32 v136, 1, v121
	v_and_b32_e32 v133, 8, v121
	v_and_b32_e32 v134, 4, v121
	v_and_b32_e32 v130, 0x200, v121
	v_and_b32_e32 v132, 0x100, v121
	v_and_b32_e32 v128, 0x800, v121
	v_and_b32_e32 v131, 0x400, v121
	v_and_b32_e32 v127, 0x20000, v121
	v_and_b32_e32 v129, 0x10000, v121
	v_and_b32_e32 v125, 0x80000, v121
	v_and_b32_e32 v126, 0x40000, v121
	v_and_b32_e32 v123, 0x2000000, v121
	v_and_b32_e32 v124, 0x1000000, v121
	v_cmp_ne_u32_e32 vcc, 0, v122
	v_add_u32_e32 v102, 0xfffff85f, v0
	v_add_u32_e32 v103, 0xfffff85e, v0
	v_med3_i32 v102, v102, 0, v233
	v_med3_i32 v103, v103, 0, v233
	v_lshl_add_u32 v102, v102, 2, s27
	v_lshl_add_u32 v103, v103, 2, s27
	v_add_u32_e32 v104, 0xfffff85d, v0
	v_add_u32_e32 v105, 0xfffff85c, v0
	ds_read_b32 v102, v102
	ds_read_b32 v103, v103
	v_med3_i32 v104, v104, 0, v233
	v_med3_i32 v105, v105, 0, v233
	v_lshl_add_u32 v104, v104, 2, s27
	v_lshl_add_u32 v105, v105, 2, s27
	v_add_u32_e32 v106, 0xfffff857, v0
	v_add_u32_e32 v107, 0xfffff856, v0
	ds_read_b32 v104, v104
	ds_read_b32 v105, v105
	v_med3_i32 v106, v106, 0, v233
	v_med3_i32 v107, v107, 0, v233
	v_add_u32_e32 v108, 0xfffff855, v0
	v_add_u32_e32 v109, 0xfffff854, v0
	v_lshl_add_u32 v106, v106, 2, s27
	v_lshl_add_u32 v107, v107, 2, s27
	v_med3_i32 v108, v108, 0, v233
	v_med3_i32 v109, v109, 0, v233
	ds_read_b32 v106, v106
	ds_read_b32 v107, v107
	v_lshl_add_u32 v108, v108, 2, s27
	v_lshl_add_u32 v109, v109, 2, s27
	v_cmp_ne_u32_e64 s[0:1], 0, v136
	ds_read_b32 v108, v108
	ds_read_b32 v109, v109
	s_waitcnt lgkmcnt(0)
	v_pk_fma_f32 v[102:103], v[50:51], s[64:65], v[102:103] op_sel_hi:[1,0,1]
	v_add_u32_e32 v110, 0xfffff84f, v0
	v_add_u32_e32 v111, 0xfffff84e, v0
	v_cndmask_b32_e64 v102, v232, v102, s[0:1]
	v_cmp_ne_u32_e64 s[0:1], 0, v135
	v_med3_i32 v110, v110, 0, v233
	v_med3_i32 v111, v111, 0, v233
	v_cndmask_b32_e64 v103, v232, v103, s[0:1]
	v_pk_fma_f32 v[104:105], v[52:53], s[64:65], v[104:105] op_sel_hi:[1,0,1]
	v_cmp_ne_u32_e64 s[0:1], 0, v134
	v_lshl_add_u32 v110, v110, 2, s27
	v_lshl_add_u32 v111, v111, 2, s27
	v_add_u32_e32 v112, 0xfffff84d, v0
	v_add_u32_e32 v113, 0xfffff84c, v0
	v_cndmask_b32_e64 v104, v232, v104, s[0:1]
	v_cmp_ne_u32_e64 s[0:1], 0, v133
	ds_read_b32 v110, v110
	ds_read_b32 v111, v111
	v_med3_i32 v112, v112, 0, v233
	v_med3_i32 v113, v113, 0, v233
	v_cndmask_b32_e64 v105, v232, v105, s[0:1]
	v_pk_fma_f32 v[106:107], v[54:55], s[64:65], v[106:107] op_sel_hi:[1,0,1]
	v_cmp_ne_u32_e64 s[0:1], 0, v132
	v_lshl_add_u32 v112, v112, 2, s27
	v_lshl_add_u32 v113, v113, 2, s27
	v_add_u32_e32 v114, 0xfffff847, v0
	v_add_u32_e32 v115, 0xfffff846, v0
	v_cndmask_b32_e64 v106, v232, v106, s[0:1]
	v_cmp_ne_u32_e64 s[0:1], 0, v130
	ds_read_b32 v112, v112
	ds_read_b32 v113, v113
	v_med3_i32 v114, v114, 0, v233
	v_med3_i32 v115, v115, 0, v233
	v_add_u32_e32 v116, 0xfffff845, v0
	v_add_u32_e32 v120, 0xfffff844, v0
	v_cndmask_b32_e64 v107, v232, v107, s[0:1]
	v_pk_fma_f32 v[108:109], v[56:57], s[64:65], v[108:109] op_sel_hi:[1,0,1]
	v_cmp_ne_u32_e64 s[0:1], 0, v131
	v_lshl_add_u32 v114, v114, 2, s27
	v_lshl_add_u32 v115, v115, 2, s27
	v_med3_i32 v116, v116, 0, v233
	v_med3_i32 v120, v120, 0, v233
	v_cndmask_b32_e64 v108, v232, v108, s[0:1]
	v_cmp_ne_u32_e64 s[0:1], 0, v128
	ds_read_b32 v114, v114
	ds_read_b32 v115, v115
	v_lshl_add_u32 v116, v116, 2, s27
	v_lshl_add_u32 v120, v120, 2, s27
	v_cndmask_b32_e64 v109, v232, v109, s[0:1]
	v_cmp_ne_u32_e64 s[0:1], 0, v129
	ds_read_b32 v116, v116
	ds_read_b32 v120, v120
	s_waitcnt lgkmcnt(0)
	v_pk_fma_f32 v[110:111], v[58:59], s[64:65], v[110:111] op_sel_hi:[1,0,1]
	v_pk_fma_f32 v[112:113], v[60:61], s[64:65], v[112:113] op_sel_hi:[1,0,1]
	v_cndmask_b32_e64 v110, v232, v110, s[0:1]
	v_cmp_ne_u32_e64 s[0:1], 0, v127
	v_pk_fma_f32 v[114:115], v[62:63], s[64:65], v[114:115] op_sel_hi:[1,0,1]
	v_fmac_f32_e32 v116, 0x3e38aa3b, v64
	v_cndmask_b32_e64 v111, v232, v111, s[0:1]
	v_cmp_ne_u32_e64 s[0:1], 0, v126
	v_cndmask_b32_e32 v116, v232, v116, vcc
	v_fmac_f32_e32 v120, 0x3e38aa3b, v65
	v_cndmask_b32_e64 v112, v232, v112, s[0:1]
	v_cmp_ne_u32_e64 s[0:1], 0, v125
	s_nop 1
	v_cndmask_b32_e64 v113, v232, v113, s[0:1]
	v_cmp_ne_u32_e64 s[0:1], 0, v124
	s_nop 1
	v_cndmask_b32_e64 v114, v232, v114, s[0:1]
	v_cmp_ne_u32_e64 s[0:1], 0, v123
	s_nop 1
	v_cndmask_b32_e64 v115, v232, v115, s[0:1]
	s_mov_b64 s[0:1], 0

; template <int DQK, int W1, int DV, int VW, int MODE> ...
;     ...
;         f32x16 e0 = s[0], e1 = s[1];
;         if (MODE != 0) { const float nm = -m; e0 = e0 + nm; e1 = e1 + nm; }
; #pragma unroll
;         for (int i = 0; i < 16; ++i) { e0[i] = __builtin_amdgcn_exp2f(e0[i]); e1[i] = __builtin_amdgcn_exp2f(e1[i]); }
;         s[0] = e0; s[1] = e1;
;         const f32x16 sm = e0 + e1;
;         typedef __attribute__((ext_vector_type(8))) float f32x8;
;         const f32x8 h8 = sm.lo + sm.hi;
;         const f32x4 h4 = h8.lo + h8.hi;
;         const f32x2 h2 = h4.lo + h4.hi;
;         l += h2[0] + h2[1];
;       }
;       bf16x8 pb[2][2];
; #pragma unroll
;       for (int n = 0; n < 2; ++n)
; #pragma unroll
;         for (int s2 = 0; s2 < 2; ++s2) {
;           u32x4 pw = {pk2(s[n][8 * s2 + 0], s[n][8 * s2 + 1]), pk2(s[n][8 * s2 + 2], s[n][8 * s2 + 3]),
;                       pk2(s[n][8 * s2 + 4], s[n][8 * s2 + 5]), pk2(s[n][8 * s2 + 6], s[n][8 * s2 + 7])};
;           pb[n][s2] = __builtin_bit_cast(bf16x8, pw);
;         }
;       pv_block<0>(o[0], bufa + vlane, pb);
;       if constexpr (NCB > 1) pv_block<1>(o[1], bufa + vlane, pb);
;       if constexpr (NCB > 2) pv_block<2>(o[2], bufa + vlane, pb);
;       if constexpr (NCB > 3) pv_block<3>(o[3], bufa + vlane, pb);
.LBB0_1344:
	v_pk_add_f32 v[34:35], v[116:117], v[98:99] op_sel_hi:[1,0] neg_lo:[0,1] neg_hi:[0,1]
	v_pk_add_f32 v[36:37], v[114:115], v[98:99] op_sel_hi:[1,0] neg_lo:[0,1] neg_hi:[0,1]
	v_pk_add_f32 v[38:39], v[112:113], v[98:99] op_sel_hi:[1,0] neg_lo:[0,1] neg_hi:[0,1]
	v_pk_add_f32 v[40:41], v[110:111], v[98:99] op_sel_hi:[1,0] neg_lo:[0,1] neg_hi:[0,1]
	v_pk_add_f32 v[42:43], v[108:109], v[98:99] op_sel_hi:[1,0] neg_lo:[0,1] neg_hi:[0,1]
	v_pk_add_f32 v[44:45], v[106:107], v[98:99] op_sel_hi:[1,0] neg_lo:[0,1] neg_hi:[0,1]
	v_pk_add_f32 v[46:47], v[104:105], v[98:99] op_sel_hi:[1,0] neg_lo:[0,1] neg_hi:[0,1]
	v_pk_add_f32 v[48:49], v[102:103], v[98:99] op_sel_hi:[1,0] neg_lo:[0,1] neg_hi:[0,1]
	v_pk_add_f32 v[64:65], v[64:65], v[98:99] op_sel_hi:[1,0] neg_lo:[0,1] neg_hi:[0,1]
	v_pk_add_f32 v[62:63], v[62:63], v[98:99] op_sel_hi:[1,0] neg_lo:[0,1] neg_hi:[0,1]
	v_pk_add_f32 v[60:61], v[60:61], v[98:99] op_sel_hi:[1,0] neg_lo:[0,1] neg_hi:[0,1]
	v_pk_add_f32 v[58:59], v[58:59], v[98:99] op_sel_hi:[1,0] neg_lo:[0,1] neg_hi:[0,1]
	v_pk_add_f32 v[56:57], v[56:57], v[98:99] op_sel_hi:[1,0] neg_lo:[0,1] neg_hi:[0,1]
	v_pk_add_f32 v[54:55], v[54:55], v[98:99] op_sel_hi:[1,0] neg_lo:[0,1] neg_hi:[0,1]
	v_pk_add_f32 v[52:53], v[52:53], v[98:99] op_sel_hi:[1,0] neg_lo:[0,1] neg_hi:[0,1]
	v_pk_add_f32 v[50:51], v[50:51], v[98:99] op_sel_hi:[1,0] neg_lo:[0,1] neg_hi:[0,1]
	v_exp_f32_e32 v48, v48
	v_exp_f32_e32 v50, v50
	v_exp_f32_e32 v49, v49
	v_exp_f32_e32 v51, v51
	v_exp_f32_e32 v46, v46
	v_exp_f32_e32 v52, v52
	v_exp_f32_e32 v47, v47
	v_exp_f32_e32 v53, v53
	v_exp_f32_e32 v44, v44
	v_exp_f32_e32 v54, v54
	v_exp_f32_e32 v45, v45
	v_exp_f32_e32 v55, v55
	v_exp_f32_e32 v42, v42
	v_exp_f32_e32 v56, v56
	v_exp_f32_e32 v43, v43
	v_exp_f32_e32 v57, v57
	v_exp_f32_e32 v102, v40
	v_exp_f32_e32 v58, v58
	v_exp_f32_e32 v103, v41
	v_exp_f32_e32 v59, v59
	v_exp_f32_e32 v104, v38
	v_exp_f32_e32 v60, v60
	v_exp_f32_e32 v105, v39
	v_exp_f32_e32 v61, v61
	v_exp_f32_e32 v36, v36
	v_exp_f32_e32 v62, v62
	v_exp_f32_e32 v37, v37
	v_exp_f32_e32 v63, v63
	v_exp_f32_e32 v34, v34
	v_exp_f32_e32 v64, v64
	v_exp_f32_e32 v35, v35
	v_exp_f32_e32 v65, v65
	v_pk_add_f32 v[38:39], v[102:103], v[58:59]
	v_pk_add_f32 v[40:41], v[104:105], v[60:61]
	v_pk_add_f32 v[106:107], v[46:47], v[52:53]
	v_pk_add_f32 v[108:109], v[34:35], v[64:65]
	v_pk_add_f32 v[110:111], v[42:43], v[56:57]
	v_pk_add_f32 v[112:113], v[36:37], v[62:63]
	v_pk_add_f32 v[114:115], v[44:45], v[54:55]
	v_pk_add_f32 v[116:117], v[48:49], v[50:51]
	v_pk_add_f32 v[112:113], v[114:115], v[112:113]
	v_pk_add_f32 v[108:109], v[110:111], v[108:109]
	v_pk_add_f32 v[40:41], v[106:107], v[40:41]
	v_pk_add_f32 v[38:39], v[116:117], v[38:39]
	v_pk_add_f32 v[40:41], v[40:41], v[108:109]
	v_pk_add_f32 v[38:39], v[38:39], v[112:113]
	s_sub_i32 s86, s86, 64
	v_pk_add_f32 v[38:39], v[38:39], v[40:41]
	v_cvt_pk_bf16_f32 v40, v44, v45
	v_add_f32_e32 v0, v38, v39
	v_cvt_pk_bf16_f32 v38, v48, v49
	v_cvt_pk_bf16_f32 v39, v46, v47
	v_cvt_pk_bf16_f32 v41, v42, v43
	v_cvt_pk_bf16_f32 v44, v36, v37
	v_cvt_pk_bf16_f32 v45, v34, v35
	v_cvt_pk_bf16_f32 v46, v50, v51
	v_cvt_pk_bf16_f32 v47, v52, v53
	v_cvt_pk_bf16_f32 v48, v54, v55
	v_cvt_pk_bf16_f32 v49, v56, v57
	v_cvt_pk_bf16_f32 v34, v58, v59
	v_cvt_pk_bf16_f32 v35, v60, v61
	v_cvt_pk_bf16_f32 v36, v62, v63
	v_cvt_pk_bf16_f32 v37, v64, v65
	v_add_f32_e32 v119, v119, v0
	v_add_u32_e32 v0, s54, v99
	ds_read_b64_tr_b16 v[62:63], v0
	ds_read_b64_tr_b16 v[64:65], v0 offset:512
	ds_read_b64_tr_b16 v[58:59], v0 offset:1024
	ds_read_b64_tr_b16 v[60:61], v0 offset:1536
	ds_read_b64_tr_b16 v[54:55], v0 offset:2048
	ds_read_b64_tr_b16 v[56:57], v0 offset:2560
	ds_read_b64_tr_b16 v[50:51], v0 offset:3072
	ds_read_b64_tr_b16 v[52:53], v0 offset:3584
	v_cvt_pk_bf16_f32 v42, v102, v103
	v_cvt_pk_bf16_f32 v43, v104, v105
	s_add_i32 s94, s94, 64
	s_waitcnt lgkmcnt(6)
	v_mfma_f32_32x32x16_bf16 v[18:33], v[62:65], v[38:41], v[18:33]
	ds_read_b64_tr_b16 v[62:63], v0 offset:4096
	ds_read_b64_tr_b16 v[64:65], v0 offset:4608
	s_waitcnt lgkmcnt(6)
	v_mfma_f32_32x32x16_bf16 v[18:33], v[58:61], v[42:45], v[18:33]
	ds_read_b64_tr_b16 v[58:59], v0 offset:5120
	ds_read_b64_tr_b16 v[60:61], v0 offset:5632
	s_waitcnt lgkmcnt(6)
	v_mfma_f32_32x32x16_bf16 v[18:33], v[54:57], v[46:49], v[18:33]
	ds_read_b64_tr_b16 v[54:55], v0 offset:6144
	ds_read_b64_tr_b16 v[56:57], v0 offset:6656
	s_waitcnt lgkmcnt(6)
	v_mfma_f32_32x32x16_bf16 v[18:33], v[50:53], v[34:37], v[18:33]
	ds_read_b64_tr_b16 v[50:51], v0 offset:7168
	ds_read_b64_tr_b16 v[52:53], v0 offset:7680
	s_cmp_ge_u32 s73, 0x1000
	s_cbranch_scc1 .Ldsa_wd
	s_cmp_ge_u32 s95, s69
	s_cbranch_scc1 .Ldsa_w0
	s_waitcnt vmcnt(2)
	s_branch .Ldsa_wd

; template <int DQK, int W1, int DV, int VW, int MODE> ...
;     ...
;   for (int t = 0; t < ntiles; ++t) {
;     const int kb = kbase0 + t * 64;
;     const unsigned bufa = lds0 + (unsigned)((t & 1) * BUF);
;     const unsigned mw0 = mwn[0], mw1 = mwn[1];
;     if (t + 1 < ntiles) stage_tile(kb + 64, (t + 1) & 1);
;     ...
;     asm volatile("s_waitcnt vmcnt(0)" ::: "memory");
;     __syncthreads();
.Ldsa_wd:
	s_add_u32 s100, s100, 0x4400
	s_cmp_eq_u32 s100, 0x11000
	s_cselect_b32 s100, 0, s100
	s_add_u32 s101, s100, 0x8800
	s_sub_u32 s0, s101, 0x11000
	s_cmp_ge_u32 s101, 0x11000
	s_cselect_b32 s101, s0, s101
	s_waitcnt lgkmcnt(0)
	s_cmp_ge_u32 s73, 0x1000
	s_cbranch_scc1 .Ldsa_nb
	s_barrier
.Ldsa_nb:
	v_mfma_f32_32x32x16_bf16 v[2:17], v[62:65], v[38:41], v[2:17]
	v_mfma_f32_32x32x16_bf16 v[2:17], v[58:61], v[42:45], v[2:17]
	v_mfma_f32_32x32x16_bf16 v[2:17], v[54:57], v[46:49], v[2:17]
	v_mfma_f32_32x32x16_bf16 v[2:17], v[50:53], v[34:37], v[2:17]
	s_cmp_lg_u32 s87, s95
	s_cbranch_scc0 .LBB0_1348
	s_mov_b32 s0, s95
	v_mov_b64_e32 v[116:117], v[100:101]
	s_add_i32 s95, s0, 1
	s_cmp_ge_u32 s0, s69
	s_cbranch_scc1 .LBB0_1333
	s_branch .LBB0_1328

; DI float bf2f(unsigned b) { return __uint_as_float(b << 16); }
; template <int DQK, int W1, int DV, int VW, int MODE> ...
;     ...
;   const float inv = __builtin_amdgcn_rcpf(xhalf_sum(l));
;   u32x2 ggv[NCB * 4];
; #pragma unroll
;   for (int cb = 0; cb < NCB; ++cb)
; #pragma unroll
;     for (int g = 0; g < 4; ++g) ggv[cb * 4 + g] = *(const u32x2*)(grow + 32 * cb + 8 * g + 4 * hi);
;   __builtin_amdgcn_sched_barrier(0);
; #pragma unroll
;   for (int cb = 0; cb < NCB; ++cb)
; #pragma unroll
;     for (int g = 0; g < 4; ++g) {
;       const int dv = 32 * cb + 8 * g + 4 * hi;
;       const u32x2 gg = ggv[cb * 4 + g];
;       float gv[4] = {bf2f(gg[0] & 0xffffu), bf2f(gg[0] >> 16), bf2f(gg[1] & 0xffffu), bf2f(gg[1] >> 16)};
;       float ov[4];
; #pragma unroll
;       for (int j = 0; j < 4; ++j) {
;         const float sg = gv[j] * __builtin_amdgcn_rcpf(1.f + __builtin_amdgcn_exp2f(-LOG2E * gv[j]));
;         ov[j] = o[cb][4 * g + j] * inv * sg;
;       }
;       *(unsigned*)((unsigned char*)yrow + dv) = pk4_fp8(ov[0] * Y_SCALE, ov[1] * Y_SCALE, ov[2] * Y_SCALE, ov[3] * Y_SCALE);
;       __builtin_amdgcn_sched_barrier(0);
;     }
.LBB0_1348:
	s_barrier
	v_mov_b64_e32 v[34:35], s[82:83]
	v_mov_b32_e32 v0, v119
	v_mad_u64_u32 v[34:35], s[0:1], v86, s34, v[34:35]
	s_nop 0
	v_permlane32_swap_b32_e32 v119, v0
	v_mad_i32_i24 v35, v87, s34, v35
	v_add_f32_e32 v54, v119, v0
	v_lshlrev_b32_e32 v0, 1, v82
	v_lshl_add_u64 v[46:47], v[34:35], 0, s[10:11]
	v_lshl_add_u64 v[34:35], v[84:85], 0, v[0:1]
	s_mov_b64 s[0:1], 0x24a0
	v_lshl_add_u64 v[48:49], v[34:35], 0, s[0:1]
	s_movk_i32 s0, 0x2000
	v_add_co_u32_e32 v34, vcc, s0, v34
	v_mov_b32_e32 v83, v1
	s_nop 0
	v_addc_co_u32_e32 v35, vcc, 0, v35, vcc
	global_load_dwordx2 v[50:51], v[34:35], off offset:1184
	global_load_dwordx2 v[52:53], v[48:49], off offset:16
	global_load_dwordx2 v[44:45], v[48:49], off offset:32
	global_load_dwordx2 v[42:43], v[48:49], off offset:48
	global_load_dwordx2 v[40:41], v[48:49], off offset:64
	global_load_dwordx2 v[38:39], v[48:49], off offset:80
	global_load_dwordx2 v[36:37], v[48:49], off offset:96
	global_load_dwordx2 v[34:35], v[48:49], off offset:112
	v_rcp_f32_e32 v0, v54
	s_waitcnt vmcnt(7)
	v_lshlrev_b32_e32 v48, 16, v50
	v_mul_f32_e32 v54, 0xbfb8aa3b, v48
	v_exp_f32_e32 v54, v54
	v_and_b32_e32 v49, 0xffff0000, v50
	v_mul_f32_e32 v18, v18, v0
	v_lshlrev_b32_e32 v50, 16, v51
	v_add_f32_e32 v54, 1.0, v54
	v_rcp_f32_e32 v54, v54
	v_mul_f32_e32 v19, v19, v0
	v_and_b32_e32 v51, 0xffff0000, v51
	v_mul_f32_e32 v20, v20, v0
	v_mul_f32_e32 v48, v54, v48
	v_mul_f32_e32 v18, v18, v48
	v_mul_f32_e32 v48, 0xbfb8aa3b, v49
	v_exp_f32_e32 v48, v48
	v_mul_f32_e32 v21, v21, v0
	v_mul_f32_e32 v18, 0x41800000, v18
	v_med3_f32 v18, v18, s93, v223
	v_add_f32_e32 v48, 1.0, v48
	v_rcp_f32_e32 v48, v48
	s_nop 0
	v_mul_f32_e32 v48, v48, v49
	v_mul_f32_e32 v19, v19, v48
	v_mul_f32_e32 v48, 0xbfb8aa3b, v50
	v_exp_f32_e32 v48, v48
	v_mul_f32_e32 v19, 0x41800000, v19
	v_med3_f32 v19, v19, s93, v223
	v_add_f32_e32 v48, 1.0, v48
	v_rcp_f32_e32 v48, v48
	s_nop 0
	v_mul_f32_e32 v48, v48, v50
	v_mul_f32_e32 v20, v20, v48
	v_mul_f32_e32 v48, 0xbfb8aa3b, v51
	v_exp_f32_e32 v48, v48
	v_mul_f32_e32 v20, 0x41800000, v20
	v_add_f32_e32 v48, 1.0, v48
	v_rcp_f32_e32 v48, v48
	s_nop 0
	v_mul_f32_e32 v48, v48, v51
	v_mul_f32_e32 v21, v21, v48
	v_mov_b32_e32 v48, v1
	v_cvt_pk_fp8_f32 v48, v18, v19
	v_mul_f32_e32 v21, 0x41800000, v21
	v_med3_f32 v18, v20, s93, v223
	v_med3_f32 v19, v21, s93, v223
	v_cvt_pk_fp8_f32 v48, v18, v19 op_sel:[0,0,1]
	v_lshl_add_u64 v[18:19], v[46:47], 0, v[82:83]
	global_store_dword v[18:19], v48, off
	s_waitcnt vmcnt(7)
	v_lshlrev_b32_e32 v20, 16, v52
	v_mul_f32_e32 v48, 0xbfb8aa3b, v20
	v_exp_f32_e32 v48, v48
	v_and_b32_e32 v21, 0xffff0000, v52
	v_mul_f32_e32 v22, v22, v0
	v_lshlrev_b32_e32 v46, 16, v53
	v_add_f32_e32 v48, 1.0, v48
	v_rcp_f32_e32 v48, v48
	v_and_b32_e32 v47, 0xffff0000, v53
	v_mul_f32_e32 v20, v48, v20
	v_mul_f32_e32 v20, v22, v20
	v_mul_f32_e32 v22, 0xbfb8aa3b, v21
	v_exp_f32_e32 v22, v22
	v_mul_f32_e32 v20, 0x41800000, v20
	v_med3_f32 v20, v20, s93, v223
	v_add_f32_e32 v22, 1.0, v22
	v_rcp_f32_e32 v22, v22
	s_nop 0
	v_mul_f32_e32 v21, v22, v21
	v_mul_f32_e32 v22, v23, v0
	v_mul_f32_e32 v21, v22, v21
	v_mul_f32_e32 v22, 0xbfb8aa3b, v46
	v_exp_f32_e32 v22, v22
	v_mul_f32_e32 v23, v24, v0
	v_mul_f32_e32 v24, v25, v0
	v_mul_f32_e32 v21, 0x41800000, v21
	v_add_f32_e32 v22, 1.0, v22
	v_rcp_f32_e32 v22, v22
	v_med3_f32 v21, v21, s93, v223
	v_mul_f32_e32 v22, v22, v46
	v_mul_f32_e32 v22, v23, v22
	v_mul_f32_e32 v23, 0xbfb8aa3b, v47
	v_exp_f32_e32 v23, v23
	v_mul_f32_e32 v22, 0x41800000, v22
	v_add_f32_e32 v23, 1.0, v23
	v_rcp_f32_e32 v23, v23
	s_nop 0
	v_mul_f32_e32 v23, v23, v47
	v_mul_f32_e32 v23, v24, v23
	v_mov_b32_e32 v24, v1
	v_cvt_pk_fp8_f32 v24, v20, v21
	v_mul_f32_e32 v23, 0x41800000, v23
	v_med3_f32 v20, v22, s93, v223
	v_med3_f32 v21, v23, s93, v223
	v_cvt_pk_fp8_f32 v24, v20, v21 op_sel:[0,0,1]
	global_store_dword v[18:19], v24, off offset:8
	s_waitcnt vmcnt(7)
	v_lshlrev_b32_e32 v20, 16, v44
	v_mul_f32_e32 v24, 0xbfb8aa3b, v20
	v_exp_f32_e32 v24, v24
	v_and_b32_e32 v21, 0xffff0000, v44
	v_lshlrev_b32_e32 v22, 16, v45
	v_and_b32_e32 v23, 0xffff0000, v45
	v_add_f32_e32 v24, 1.0, v24
	v_rcp_f32_e32 v24, v24
	s_nop 0
	v_mul_f32_e32 v20, v24, v20
	v_mul_f32_e32 v24, v26, v0
	v_mul_f32_e32 v20, v24, v20
	v_mul_f32_e32 v24, 0xbfb8aa3b, v21
	v_exp_f32_e32 v24, v24
	v_mul_f32_e32 v20, 0x41800000, v20
	v_med3_f32 v20, v20, s93, v223
	v_add_f32_e32 v24, 1.0, v24
	v_rcp_f32_e32 v24, v24
	s_nop 0
	v_mul_f32_e32 v21, v24, v21
	v_mul_f32_e32 v24, v27, v0
	v_mul_f32_e32 v21, v24, v21
	v_mul_f32_e32 v24, 0xbfb8aa3b, v22
	v_exp_f32_e32 v24, v24
	v_mul_f32_e32 v21, 0x41800000, v21
	v_med3_f32 v21, v21, s93, v223
	v_add_f32_e32 v24, 1.0, v24
	v_rcp_f32_e32 v24, v24
	s_nop 0
	v_mul_f32_e32 v22, v24, v22
	v_mul_f32_e32 v24, v28, v0
	v_mul_f32_e32 v22, v24, v22
	v_mul_f32_e32 v24, 0xbfb8aa3b, v23
	v_exp_f32_e32 v24, v24
	v_mul_f32_e32 v22, 0x41800000, v22
	v_add_f32_e32 v24, 1.0, v24
	v_rcp_f32_e32 v24, v24
	s_nop 0
	v_mul_f32_e32 v23, v24, v23
	v_mul_f32_e32 v24, v29, v0
	v_mul_f32_e32 v23, v24, v23
	v_mov_b32_e32 v24, v1
	v_cvt_pk_fp8_f32 v24, v20, v21
	v_mul_f32_e32 v23, 0x41800000, v23
	v_med3_f32 v20, v22, s93, v223
	v_med3_f32 v21, v23, s93, v223
	v_cvt_pk_fp8_f32 v24, v20, v21 op_sel:[0,0,1]
	global_store_dword v[18:19], v24, off offset:16
	s_waitcnt vmcnt(7)
; DI float bf2f(unsigned b) { return __uint_as_float(b << 16); }
; template <int DQK, int W1, int DV, int VW, int MODE> ...
;     ...
; #pragma unroll
;   for (int cb = 0; cb < NCB; ++cb)
; #pragma unroll
;     for (int g = 0; g < 4; ++g) {
;       const int dv = 32 * cb + 8 * g + 4 * hi;
;       const u32x2 gg = ggv[cb * 4 + g];
;       float gv[4] = {bf2f(gg[0] & 0xffffu), bf2f(gg[0] >> 16), bf2f(gg[1] & 0xffffu), bf2f(gg[1] >> 16)};
;       float ov[4];
; #pragma unroll
;       for (int j = 0; j < 4; ++j) {
;         const float sg = gv[j] * __builtin_amdgcn_rcpf(1.f + __builtin_amdgcn_exp2f(-LOG2E * gv[j]));
;         ov[j] = o[cb][4 * g + j] * inv * sg;
;       }
;       *(unsigned*)((unsigned char*)yrow + dv) = pk4_fp8(ov[0] * Y_SCALE, ov[1] * Y_SCALE, ov[2] * Y_SCALE, ov[3] * Y_SCALE);
;       __builtin_amdgcn_sched_barrier(0);
;     }
	v_lshlrev_b32_e32 v20, 16, v42
	v_mul_f32_e32 v24, 0xbfb8aa3b, v20
	v_exp_f32_e32 v24, v24
	v_and_b32_e32 v21, 0xffff0000, v42
	v_lshlrev_b32_e32 v22, 16, v43
	v_and_b32_e32 v23, 0xffff0000, v43
	v_add_f32_e32 v24, 1.0, v24
	v_rcp_f32_e32 v24, v24
	s_nop 0
	v_mul_f32_e32 v20, v24, v20
	v_mul_f32_e32 v24, v30, v0
	v_mul_f32_e32 v20, v24, v20
	v_mul_f32_e32 v24, 0xbfb8aa3b, v21
	v_exp_f32_e32 v24, v24
	v_mul_f32_e32 v20, 0x41800000, v20
	v_med3_f32 v20, v20, s93, v223
	v_add_f32_e32 v24, 1.0, v24
	v_rcp_f32_e32 v24, v24
	s_nop 0
	v_mul_f32_e32 v21, v24, v21
	v_mul_f32_e32 v24, v31, v0
	v_mul_f32_e32 v21, v24, v21
	v_mul_f32_e32 v24, 0xbfb8aa3b, v22
	v_exp_f32_e32 v24, v24
	v_mul_f32_e32 v21, 0x41800000, v21
	v_med3_f32 v21, v21, s93, v223
	v_add_f32_e32 v24, 1.0, v24
	v_rcp_f32_e32 v24, v24
	s_nop 0
	v_mul_f32_e32 v22, v24, v22
	v_mul_f32_e32 v24, v32, v0
	v_mul_f32_e32 v22, v24, v22
	v_mul_f32_e32 v24, 0xbfb8aa3b, v23
	v_exp_f32_e32 v24, v24
	v_mul_f32_e32 v22, 0x41800000, v22
	v_add_f32_e32 v24, 1.0, v24
	v_rcp_f32_e32 v24, v24
	s_nop 0
	v_mul_f32_e32 v23, v24, v23
	v_mul_f32_e32 v24, v33, v0
	v_mul_f32_e32 v23, v24, v23
	v_mov_b32_e32 v24, v1
	v_cvt_pk_fp8_f32 v24, v20, v21
	v_mul_f32_e32 v23, 0x41800000, v23
	v_med3_f32 v20, v22, s93, v223
	v_med3_f32 v21, v23, s93, v223
	v_cvt_pk_fp8_f32 v24, v20, v21 op_sel:[0,0,1]
	global_store_dword v[18:19], v24, off offset:24
	s_waitcnt vmcnt(7)
	v_lshlrev_b32_e32 v20, 16, v40
	v_mul_f32_e32 v24, 0xbfb8aa3b, v20
	v_exp_f32_e32 v24, v24
	v_and_b32_e32 v21, 0xffff0000, v40
	v_mul_f32_e32 v2, v2, v0
	v_lshlrev_b32_e32 v22, 16, v41
	v_add_f32_e32 v24, 1.0, v24
	v_rcp_f32_e32 v24, v24
	v_mul_f32_e32 v3, v3, v0
	v_and_b32_e32 v23, 0xffff0000, v41
	v_mul_f32_e32 v4, v4, v0
	v_mul_f32_e32 v20, v24, v20
	v_mul_f32_e32 v2, v2, v20
	v_mul_f32_e32 v20, 0xbfb8aa3b, v21
	v_exp_f32_e32 v20, v20
	v_mul_f32_e32 v5, v5, v0
	v_mul_f32_e32 v2, 0x41800000, v2
	v_med3_f32 v2, v2, s93, v223
	v_add_f32_e32 v20, 1.0, v20
	v_rcp_f32_e32 v20, v20
	s_nop 0
	v_mul_f32_e32 v20, v20, v21
	v_mul_f32_e32 v3, v3, v20
	v_mul_f32_e32 v20, 0xbfb8aa3b, v22
	v_exp_f32_e32 v20, v20
	v_mul_f32_e32 v3, 0x41800000, v3
	v_med3_f32 v3, v3, s93, v223
	v_add_f32_e32 v20, 1.0, v20
	v_rcp_f32_e32 v20, v20
	s_nop 0
	v_mul_f32_e32 v20, v20, v22
	v_mul_f32_e32 v4, v4, v20
	v_mul_f32_e32 v20, 0xbfb8aa3b, v23
	v_exp_f32_e32 v20, v20
	v_mul_f32_e32 v4, 0x41800000, v4
	v_add_f32_e32 v20, 1.0, v20
	v_rcp_f32_e32 v20, v20
	s_nop 0
	v_mul_f32_e32 v20, v20, v23
	v_mul_f32_e32 v5, v5, v20
	v_mov_b32_e32 v20, v1
	v_cvt_pk_fp8_f32 v20, v2, v3
	v_mul_f32_e32 v5, 0x41800000, v5
	v_med3_f32 v2, v4, s93, v223
	v_med3_f32 v3, v5, s93, v223
	v_cvt_pk_fp8_f32 v20, v2, v3 op_sel:[0,0,1]
	global_store_dword v[18:19], v20, off offset:32
	s_waitcnt vmcnt(7)
	v_lshlrev_b32_e32 v2, 16, v38
	v_mul_f32_e32 v20, 0xbfb8aa3b, v2
	v_exp_f32_e32 v20, v20
	v_and_b32_e32 v3, 0xffff0000, v38
	v_mul_f32_e32 v6, v6, v0
	v_lshlrev_b32_e32 v4, 16, v39
	v_add_f32_e32 v20, 1.0, v20
	v_rcp_f32_e32 v20, v20
	v_and_b32_e32 v5, 0xffff0000, v39
	v_mul_f32_e32 v2, v20, v2
	v_mul_f32_e32 v2, v6, v2
	v_mul_f32_e32 v6, 0xbfb8aa3b, v3
	v_exp_f32_e32 v6, v6
	v_mul_f32_e32 v2, 0x41800000, v2
	v_med3_f32 v2, v2, s93, v223
	v_add_f32_e32 v6, 1.0, v6
	v_rcp_f32_e32 v6, v6
	s_nop 0
	v_mul_f32_e32 v3, v6, v3
	v_mul_f32_e32 v6, v7, v0
	v_mul_f32_e32 v3, v6, v3
	v_mul_f32_e32 v6, 0xbfb8aa3b, v4
	v_exp_f32_e32 v6, v6
	v_mul_f32_e32 v3, 0x41800000, v3
	v_med3_f32 v3, v3, s93, v223
	v_add_f32_e32 v6, 1.0, v6
	v_rcp_f32_e32 v6, v6
	s_nop 0
	v_mul_f32_e32 v4, v6, v4
	v_mul_f32_e32 v6, v8, v0
	v_mul_f32_e32 v4, v6, v4
	v_mul_f32_e32 v6, 0xbfb8aa3b, v5
	v_exp_f32_e32 v6, v6
	v_mul_f32_e32 v4, 0x41800000, v4
	v_add_f32_e32 v6, 1.0, v6
	v_rcp_f32_e32 v6, v6
	s_nop 0
	v_mul_f32_e32 v5, v6, v5
	v_mul_f32_e32 v6, v9, v0
	v_mul_f32_e32 v5, v6, v5
	v_mov_b32_e32 v6, v1
	v_cvt_pk_fp8_f32 v6, v2, v3
	v_mul_f32_e32 v5, 0x41800000, v5
	v_med3_f32 v2, v4, s93, v223
	v_med3_f32 v3, v5, s93, v223
	v_cvt_pk_fp8_f32 v6, v2, v3 op_sel:[0,0,1]
	global_store_dword v[18:19], v6, off offset:40
	s_waitcnt vmcnt(7)
	v_lshlrev_b32_e32 v2, 16, v36
	v_mul_f32_e32 v6, 0xbfb8aa3b, v2
	v_exp_f32_e32 v6, v6
	v_and_b32_e32 v3, 0xffff0000, v36
	v_lshlrev_b32_e32 v4, 16, v37
	v_and_b32_e32 v5, 0xffff0000, v37
	v_add_f32_e32 v6, 1.0, v6
	v_rcp_f32_e32 v6, v6
	s_nop 0
	v_mul_f32_e32 v2, v6, v2
	v_mul_f32_e32 v6, v10, v0
	v_mul_f32_e32 v2, v6, v2
	v_mul_f32_e32 v6, 0xbfb8aa3b, v3
	v_exp_f32_e32 v6, v6
	v_mul_f32_e32 v2, 0x41800000, v2
	v_med3_f32 v2, v2, s93, v223
	v_add_f32_e32 v6, 1.0, v6
	v_rcp_f32_e32 v6, v6
	s_nop 0
	v_mul_f32_e32 v3, v6, v3
	v_mul_f32_e32 v6, v11, v0
	v_mul_f32_e32 v3, v6, v3
	v_mul_f32_e32 v6, 0xbfb8aa3b, v4
	v_exp_f32_e32 v6, v6
	v_mul_f32_e32 v3, 0x41800000, v3
	v_med3_f32 v3, v3, s93, v223
	v_add_f32_e32 v6, 1.0, v6
	v_rcp_f32_e32 v6, v6
	s_nop 0
	v_mul_f32_e32 v4, v6, v4
	v_mul_f32_e32 v6, v12, v0
	v_mul_f32_e32 v4, v6, v4
	v_mul_f32_e32 v6, 0xbfb8aa3b, v5
	v_exp_f32_e32 v6, v6
	v_mul_f32_e32 v4, 0x41800000, v4
	v_add_f32_e32 v6, 1.0, v6
	v_rcp_f32_e32 v6, v6
	s_nop 0
	v_mul_f32_e32 v5, v6, v5
	v_mul_f32_e32 v6, v13, v0
	v_mul_f32_e32 v5, v6, v5
	v_mov_b32_e32 v6, v1
	v_cvt_pk_fp8_f32 v6, v2, v3
	v_mul_f32_e32 v5, 0x41800000, v5
	v_med3_f32 v2, v4, s93, v223
	v_med3_f32 v3, v5, s93, v223
	v_cvt_pk_fp8_f32 v6, v2, v3 op_sel:[0,0,1]
	global_store_dword v[18:19], v6, off offset:48
	s_waitcnt vmcnt(7)
	v_lshlrev_b32_e32 v2, 16, v34
	v_mul_f32_e32 v6, 0xbfb8aa3b, v2
	v_exp_f32_e32 v6, v6
	v_and_b32_e32 v3, 0xffff0000, v34
	v_lshlrev_b32_e32 v4, 16, v35
	v_and_b32_e32 v5, 0xffff0000, v35
	v_add_f32_e32 v6, 1.0, v6
	v_rcp_f32_e32 v6, v6
	s_nop 0
	v_mul_f32_e32 v2, v6, v2
	v_mul_f32_e32 v6, v14, v0
	v_mul_f32_e32 v2, v6, v2
	v_mul_f32_e32 v6, 0xbfb8aa3b, v3
	v_exp_f32_e32 v6, v6
	v_mul_f32_e32 v2, 0x41800000, v2
	v_med3_f32 v2, v2, s93, v223
	v_add_f32_e32 v6, 1.0, v6
	v_rcp_f32_e32 v6, v6
	s_nop 0
	v_mul_f32_e32 v3, v6, v3
	v_mul_f32_e32 v6, v15, v0
	v_mul_f32_e32 v3, v6, v3
	v_mul_f32_e32 v6, 0xbfb8aa3b, v4
	v_exp_f32_e32 v6, v6
	v_mul_f32_e32 v3, 0x41800000, v3
	v_med3_f32 v3, v3, s93, v223
	v_add_f32_e32 v6, 1.0, v6
	v_rcp_f32_e32 v6, v6
	s_nop 0
	v_mul_f32_e32 v4, v6, v4
	v_mul_f32_e32 v6, v16, v0
	v_mul_f32_e32 v4, v6, v4
	v_mul_f32_e32 v6, 0xbfb8aa3b, v5
	v_exp_f32_e32 v6, v6
	v_mul_f32_e32 v0, v17, v0
	v_mul_f32_e32 v4, 0x41800000, v4
	v_add_f32_e32 v6, 1.0, v6
	v_rcp_f32_e32 v6, v6
	s_nop 0
	v_mul_f32_e32 v5, v6, v5
	v_mul_f32_e32 v0, v0, v5
	v_mov_b32_e32 v5, v1
	v_cvt_pk_fp8_f32 v5, v2, v3
	v_mul_f32_e32 v0, 0x41800000, v0
	v_med3_f32 v2, v4, s93, v223
	v_med3_f32 v0, v0, s93, v223
	v_cvt_pk_fp8_f32 v5, v2, v0 op_sel:[0,0,1]
	global_store_dword v[18:19], v5, off offset:56
	s_movk_i32 s20, 0x600
	s_mov_b32 s86, 0x800000
	s_movk_i32 s87, 0x3fff
	v_readlane_b32 s3, v254, 29
